# ssm_a: hoist loop-invariant g2 gain loads out of chunk loop; 16-step recurrence with batched LDS preload + 4 f32 FMAs per step
# speedup vs baseline: 1.0057x; 1.0057x over previous
.LBB0_292:
	s_or_b64 exec, exec, s[0:1]
	s_waitcnt vmcnt(0)
	v_mul_f32_e32 v20, v50, v14
	v_mul_f32_e32 v14, 0x3fb8aa3b, v20
	s_mov_b32 s0, 0x3fb8aa3b
	v_fma_f32 v21, v20, s0, -v14
	v_rndne_f32_e32 v22, v14
	v_fmac_f32_e32 v21, 0x32a5705f, v20
	v_sub_f32_e32 v14, v14, v22
	v_add_f32_e32 v14, v14, v21
	v_exp_f32_e32 v14, v14
	v_cvt_i32_f32_e32 v21, v22
	s_mov_b32 s0, 0xc2ce8ed0
	v_cmp_ngt_f32_e32 vcc, s0, v20
	s_mov_b32 s0, 0x42b17218
	v_ldexp_f32 v14, v14, v21
	v_cndmask_b32_e32 v14, 0, v14, vcc
	v_cmp_nlt_f32_e32 vcc, s0, v20
	s_movk_i32 s27, 0x1f8
	s_load_dwordx4 s[28:31], s[80:81], 0x70
	v_cndmask_b32_e32 v14, v196, v14, vcc
	v_cmp_class_f32_e64 vcc, v12, s27
	v_xor_b32_e32 v12, v13, v12
	v_and_b32_e32 v13, 1, v16
	v_cmp_eq_u32_e64 s[0:1], 0, v13
	v_mul_f32_e32 v13, v15, v15
	v_fmamk_f32 v23, v13, 0xb94c1982, v191
	v_fmaak_f32 v23, v13, v23, 0xbe2aaa9d
	v_mul_f32_e32 v23, v13, v23
	v_fmac_f32_e32 v15, v15, v23
	v_fmamk_f32 v23, v13, 0x37d75334, v192
	v_fmaak_f32 v23, v13, v23, 0x3d2aabf7
	v_fmaak_f32 v23, v13, v23, 0xbf000004
	v_fma_f32 v13, v13, v23, 1.0
	v_cndmask_b32_e64 v23, v13, v15, s[0:1]
	v_lshlrev_b32_e32 v16, 30, v16
	v_xor_b32_e32 v15, 0x80000000, v15
	v_and_b32_e32 v16, 0x80000000, v16
	v_xor_b32_e32 v12, v12, v23
	v_cndmask_b32_e64 v13, v15, v13, s[0:1]
	v_xor_b32_e32 v13, v13, v16
	v_xor_b32_e32 v12, v12, v16
	v_cndmask_b32_e32 v13, v199, v13, vcc
	v_cndmask_b32_e32 v12, v199, v12, vcc
	v_pk_mul_f32 v[48:49], v[14:15], v[12:13] op_sel_hi:[0,1]
	v_mul_f32_e32 v12, v0, v0
	v_fmamk_f32 v14, v12, 0xb94c1982, v191
	v_fmaak_f32 v14, v12, v14, 0xbe2aaa9d
	v_mul_f32_e32 v14, v12, v14
	v_fmac_f32_e32 v0, v0, v14
	v_fmamk_f32 v14, v12, 0x37d75334, v192
	v_fmaak_f32 v14, v12, v14, 0x3d2aabf7
	v_fmaak_f32 v14, v12, v14, 0xbf000004
	v_and_b32_e32 v15, 1, v19
	v_fma_f32 v12, v12, v14, 1.0
	v_lshlrev_b32_e32 v14, 30, v19
	v_cmp_eq_u32_e32 vcc, 0, v15
	v_and_b32_e32 v14, 0x80000000, v14
	s_mov_b32 s0, 0x43000000
	v_cndmask_b32_e32 v0, v12, v0, vcc
	v_xor_b32_e32 v12, v18, v17
	v_xor_b32_e32 v12, v12, v14
	v_xor_b32_e32 v0, v12, v0
	v_fmamk_f32 v12, v22, 0xbf317218, v20
	v_fmac_f32_e32 v12, 0x3102e308, v22
	v_fmamk_f32 v14, v12, 0x395133b1, v193
	v_fmaak_f32 v14, v12, v14, 0x3c0887f9
	v_fmaak_f32 v14, v12, v14, 0x3d2aaa81
	v_fmaak_f32 v14, v12, v14, 0x3e2aaaab
	v_fma_f32 v14, v12, v14, 0.5
	v_cmp_class_f32_e64 vcc, v17, s27
	v_mul_f32_e32 v14, v12, v14
	v_fmac_f32_e32 v12, v12, v14
	v_cndmask_b32_e32 v0, v199, v0, vcc
	v_cmp_eq_f32_e32 vcc, s0, v22
	v_ldexp_f32 v14, 1.0, v21
	s_mov_b32 s0, 0x42b17217
	v_cndmask_b32_e32 v14, v14, v200, vcc
	v_add_f32_e32 v15, -1.0, v14
	v_fmac_f32_e32 v15, v14, v12
	v_add_f32_e32 v12, v15, v15
	v_cndmask_b32_e32 v12, v15, v12, vcc
	v_cmp_nlt_f32_e32 vcc, s0, v20
	s_mov_b32 s0, 0xc1880000
	v_add_f32_e32 v14, v0, v0
	v_cndmask_b32_e32 v12, v196, v12, vcc
	v_cmp_ngt_f32_e32 vcc, s0, v20
	v_mul_f32_e32 v0, v0, v14
	v_lshlrev_b64 v[10:11], 6, v[10:11]
	v_cndmask_b32_e32 v12, -1.0, v12, vcc
	v_fma_f32 v0, v12, v13, -v0
	v_pk_mul_f32 v[12:13], v[50:51], v[50:51]
	s_waitcnt lgkmcnt(0)
	v_lshl_add_u64 v[38:39], s[30:31], 0, v[10:11]
	v_add_f32_e32 v12, v12, v13
	v_div_scale_f32 v13, s[0:1], v12, v12, 1.0
	v_rcp_f32_e32 v14, v13
	v_mov_b32_e32 v66, v51
	v_mov_b32_e32 v67, v50
	v_mov_b32_e32 v64, v51
	v_fma_f32 v15, -v13, v14, 1.0
	v_fmac_f32_e32 v14, v15, v14
	v_div_scale_f32 v15, vcc, 1.0, v12, 1.0
	v_mul_f32_e32 v16, v15, v14
	v_fma_f32 v17, -v13, v16, v15
	v_fmac_f32_e32 v16, v17, v14
	v_fma_f32 v13, -v13, v16, v15
	v_div_fmas_f32 v13, v13, v14, v16
	v_lshl_add_u64 v[14:15], s[28:29], 0, v[10:11]
	v_div_fixup_f32 v52, v13, v12, 1.0
	global_load_dwordx4 v[10:13], v[14:15], off offset:48
	global_load_dwordx4 v[18:21], v[14:15], off offset:32
	global_load_dwordx4 v[26:29], v[14:15], off offset:16
	global_load_dwordx4 v[34:37], v[14:15], off
	s_nop 0
	global_load_dwordx4 v[14:17], v[38:39], off offset:48
	global_load_dwordx4 v[22:25], v[38:39], off offset:32
	global_load_dwordx4 v[30:33], v[38:39], off offset:16
	s_nop 0
	global_load_dwordx4 v[38:41], v[38:39], off
	v_pk_mul_f32 v[68:69], v[66:67], v[0:1] op_sel:[1,0] op_sel_hi:[0,0]
	v_pk_fma_f32 v[64:65], v[64:65], v[48:49], v[68:69]
	v_pk_fma_f32 v[66:67], v[66:67], v[48:49], v[68:69] op_sel_hi:[1,0,1] neg_lo:[0,0,1] neg_hi:[0,0,1]
	s_waitcnt lgkmcnt(0)
	s_lshl_b32 s88, s3, 2
	v_mov_b32_e32 v65, v67
	v_pk_mul_f32 v[64:65], v[52:53], v[64:65] op_sel_hi:[0,1]
	s_mov_b32 s2, 0
	v_mov_b32_e32 v50, v48
	v_mov_b32_e32 v51, v48
	s_or_b32 s0, s26, 64
	s_waitcnt vmcnt(4)
	v_mov_b32_e32 v66, v34
	s_waitcnt vmcnt(0)
	v_mov_b32_e32 v67, v38
	v_pk_mul_f32 v[66:67], v[66:67], v[64:65]
	s_nop 0
	v_sub_f32_e32 v0, v66, v67
	v_mov_b32_e32 v66, v38
	v_mov_b32_e32 v67, v34
	v_mov_b32_e32 v34, v39
	v_pk_mul_f32 v[66:67], v[66:67], v[64:65]
	v_mov_b32_e32 v38, v35
	v_pk_mul_f32 v[34:35], v[34:35], v[64:65]
	v_add_f32_e32 v52, v66, v67
	v_pk_mul_f32 v[66:67], v[38:39], v[64:65]
	v_add_f32_e32 v39, v34, v35
	v_mov_b32_e32 v34, v36
	v_mov_b32_e32 v35, v40
	v_pk_mul_f32 v[34:35], v[34:35], v[64:65]
	v_sub_f32_e32 v38, v66, v67
	v_sub_f32_e32 v66, v34, v35
	v_mov_b32_e32 v34, v40
	v_mov_b32_e32 v35, v36
	v_pk_mul_f32 v[34:35], v[34:35], v[64:65]
	v_mov_b32_e32 v40, v37
	v_add_f32_e32 v67, v34, v35
	v_pk_mul_f32 v[34:35], v[40:41], v[64:65]
	v_mov_b32_e32 v36, v41
	v_sub_f32_e32 v40, v34, v35
	v_pk_mul_f32 v[34:35], v[36:37], v[64:65]
	s_nop 0
	v_add_f32_e32 v36, v34, v35
	v_mov_b32_e32 v34, v26
	v_mov_b32_e32 v35, v30
	v_pk_mul_f32 v[34:35], v[34:35], v[64:65]
	s_nop 0
	v_sub_f32_e32 v37, v34, v35
	v_mov_b32_e32 v34, v30
	v_mov_b32_e32 v35, v26
	v_mov_b32_e32 v26, v31
	v_pk_mul_f32 v[34:35], v[34:35], v[64:65]
	v_mov_b32_e32 v30, v27
	v_pk_mul_f32 v[26:27], v[26:27], v[64:65]
	v_add_f32_e32 v41, v34, v35
	v_pk_mul_f32 v[34:35], v[30:31], v[64:65]
	v_add_f32_e32 v31, v26, v27
	v_mov_b32_e32 v26, v28
	v_mov_b32_e32 v27, v32
	v_pk_mul_f32 v[26:27], v[26:27], v[64:65]
	v_sub_f32_e32 v30, v34, v35
	v_sub_f32_e32 v34, v26, v27
	v_mov_b32_e32 v26, v32
	v_mov_b32_e32 v27, v28
	v_pk_mul_f32 v[26:27], v[26:27], v[64:65]
	v_mov_b32_e32 v32, v29
	v_add_f32_e32 v35, v26, v27
	v_pk_mul_f32 v[26:27], v[32:33], v[64:65]
	v_mov_b32_e32 v28, v33
	v_sub_f32_e32 v32, v26, v27
	v_pk_mul_f32 v[26:27], v[28:29], v[64:65]
	s_nop 0
	v_add_f32_e32 v28, v26, v27
	v_mov_b32_e32 v26, v18
	v_mov_b32_e32 v27, v22
	v_pk_mul_f32 v[26:27], v[26:27], v[64:65]
	s_nop 0
	v_sub_f32_e32 v29, v26, v27
	v_mov_b32_e32 v26, v22
	v_mov_b32_e32 v27, v18
	v_mov_b32_e32 v18, v23
	v_pk_mul_f32 v[26:27], v[26:27], v[64:65]
	v_mov_b32_e32 v22, v19
	v_pk_mul_f32 v[18:19], v[18:19], v[64:65]
	v_add_f32_e32 v33, v26, v27
	v_pk_mul_f32 v[26:27], v[22:23], v[64:65]
	v_add_f32_e32 v23, v18, v19
	v_mov_b32_e32 v18, v20
	v_mov_b32_e32 v19, v24
	v_pk_mul_f32 v[18:19], v[18:19], v[64:65]
	v_sub_f32_e32 v22, v26, v27
	v_sub_f32_e32 v26, v18, v19
	v_mov_b32_e32 v18, v24
	v_mov_b32_e32 v19, v20
	v_pk_mul_f32 v[18:19], v[18:19], v[64:65]
	v_mov_b32_e32 v24, v21
	v_add_f32_e32 v27, v18, v19
	v_pk_mul_f32 v[18:19], v[24:25], v[64:65]
	v_mov_b32_e32 v20, v25
	v_sub_f32_e32 v24, v18, v19
	v_pk_mul_f32 v[18:19], v[20:21], v[64:65]
	s_nop 0
	v_add_f32_e32 v25, v18, v19
	v_mov_b32_e32 v18, v10
	v_mov_b32_e32 v19, v14
	v_pk_mul_f32 v[18:19], v[18:19], v[64:65]
	s_nop 0
	v_sub_f32_e32 v20, v18, v19
	v_mov_b32_e32 v19, v10
	v_mov_b32_e32 v10, v15
	v_mov_b32_e32 v18, v14
	v_mov_b32_e32 v14, v11
	v_pk_mul_f32 v[10:11], v[10:11], v[64:65]
	v_pk_mul_f32 v[18:19], v[18:19], v[64:65]
	v_add_f32_e32 v69, v10, v11
	v_mov_b32_e32 v10, v12
	v_mov_b32_e32 v11, v16
	v_add_f32_e32 v68, v18, v19
	v_pk_mul_f32 v[18:19], v[14:15], v[64:65]
	v_pk_mul_f32 v[10:11], v[10:11], v[64:65]
	v_sub_f32_e32 v18, v18, v19
	v_sub_f32_e32 v19, v10, v11
	v_mov_b32_e32 v10, v16
	v_mov_b32_e32 v11, v12
	v_pk_mul_f32 v[10:11], v[10:11], v[64:65]
	v_mov_b32_e32 v16, v13
	v_add_f32_e32 v70, v10, v11
	v_pk_mul_f32 v[10:11], v[16:17], v[64:65]
	v_mov_b32_e32 v12, v17
	v_sub_f32_e32 v21, v10, v11
	v_pk_mul_f32 v[10:11], v[12:13], v[64:65]
	s_nop 0
	v_add_f32_e32 v64, v10, v11
	v_cvt_pk_bf16_f32 v10, v0, v38
	v_cvt_pk_bf16_f32 v11, v66, v40
	v_cvt_pk_bf16_f32 v12, v37, v30
	v_cvt_pk_bf16_f32 v13, v34, v32
	v_add_u32_e32 v0, s23, v56
	v_cvt_pk_bf16_f32 v14, v29, v22
	v_cvt_pk_bf16_f32 v15, v26, v24
	v_cvt_pk_bf16_f32 v16, v20, v18
	v_cvt_pk_bf16_f32 v17, v19, v21
	v_cvt_pk_bf16_f32 v18, v52, v39
	v_cvt_pk_bf16_f32 v19, v67, v36
	v_cvt_pk_bf16_f32 v20, v41, v31
	v_cvt_pk_bf16_f32 v21, v35, v28
	v_cvt_pk_bf16_f32 v22, v33, v23
	v_cvt_pk_bf16_f32 v23, v27, v25
	v_cvt_pk_bf16_f32 v24, v68, v69
	v_cvt_pk_bf16_f32 v25, v70, v64
	ds_write_b128 v0, v[10:13] offset:17408
	ds_write_b128 v0, v[14:17] offset:17424
	ds_write_b128 v0, v[18:21] offset:19456
	ds_write_b128 v0, v[22:25] offset:19472
	s_waitcnt lgkmcnt(0)
	ds_read2st64_b64 v[10:13], v57 offset0:34 offset1:35
	ds_read2st64_b64 v[14:17], v57 offset0:36 offset1:37
	ds_read2st64_b64 v[18:21], v57 offset0:38 offset1:39
	ds_read2st64_b64 v[22:25], v57 offset0:40 offset1:41
	s_waitcnt lgkmcnt(0)
	v_mov_b32_e32 v0, v1
	v_lshl_add_u64 v[26:27], v[44:45], 0, s[88:89]
	global_load_dwordx4 v[116:119], v[26:27], off offset:16
	global_load_dwordx4 v[120:123], v[26:27], off
	v_mov_b32_e32 v28, v49
	v_mov_b32_e32 v29, v49
	v_pk_mov_b32 v[30:31], v[48:49], v[48:49] op_sel:[1,0]
	v_mov_b64_e32 v[32:33], v[0:1]
.LBB0_293:
	s_waitcnt lgkmcnt(0)
	s_barrier
	s_waitcnt vmcnt(0)
	v_lshlrev_b32_e32 v0, 16, v2
	s_cmp_eq_u32 s2, 7
	v_mul_f32_e32 v0, v120, v0
	v_and_b32_e32 v38, 0xffff0000, v2
	v_mul_f32_e32 v38, v121, v38
	v_cvt_pk_bf16_f32 v38, v0, v38
	v_lshlrev_b32_e32 v0, 16, v3
	v_and_b32_e32 v39, 0xffff0000, v3
	v_mul_f32_e32 v0, v122, v0
	v_mul_f32_e32 v39, v123, v39
	v_cvt_pk_bf16_f32 v39, v0, v39
	v_lshlrev_b32_e32 v0, 16, v4
	v_mul_f32_e32 v0, v116, v0
	v_and_b32_e32 v34, 0xffff0000, v4
	v_mul_f32_e32 v34, v117, v34
	v_cvt_pk_bf16_f32 v40, v0, v34
	v_lshlrev_b32_e32 v0, 16, v5
	v_and_b32_e32 v34, 0xffff0000, v5
	v_mul_f32_e32 v0, v118, v0
	v_mul_f32_e32 v34, v119, v34
	v_cvt_pk_bf16_f32 v41, v0, v34
	ds_write_b128 v59, v[38:41]
	v_lshlrev_b32_e32 v0, 16, v6
	v_mul_f32_e32 v0, v120, v0
	v_and_b32_e32 v38, 0xffff0000, v6
	v_mul_f32_e32 v38, v121, v38
	v_cvt_pk_bf16_f32 v38, v0, v38
	v_lshlrev_b32_e32 v0, 16, v7
	v_and_b32_e32 v39, 0xffff0000, v7
	v_mul_f32_e32 v0, v122, v0
	v_mul_f32_e32 v39, v123, v39
	v_cvt_pk_bf16_f32 v39, v0, v39
	v_lshlrev_b32_e32 v0, 16, v8
	v_mul_f32_e32 v0, v116, v0
	v_and_b32_e32 v34, 0xffff0000, v8
	v_mul_f32_e32 v34, v117, v34
	v_cvt_pk_bf16_f32 v40, v0, v34
	v_lshlrev_b32_e32 v0, 16, v9
	v_and_b32_e32 v34, 0xffff0000, v9
	v_mul_f32_e32 v0, v118, v0
	v_mul_f32_e32 v34, v119, v34
	v_cvt_pk_bf16_f32 v41, v0, v34
	ds_write_b128 v60, v[38:41]
	s_cbranch_scc1 .LBB0_295
	s_lshl_b32 s1, s2, 6
	s_add_i32 s1, s1, s0
	v_add_u32_e32 v2, s1, v53
	v_add_u32_e32 v4, s1, v54
	v_ashrrev_i32_e32 v3, 31, v2
	v_ashrrev_i32_e32 v5, 31, v4
	v_lshlrev_b64 v[2:3], 11, v[2:3]
	v_lshlrev_b64 v[4:5], 11, v[4:5]
	v_lshl_add_u64 v[2:3], v[46:47], 0, v[2:3]
	v_lshl_add_u64 v[6:7], v[46:47], 0, v[4:5]
	global_load_dwordx4 v[2:5], v[2:3], off
	s_nop 0
	global_load_dwordx4 v[6:9], v[6:7], off

.LBB0_296:
	v_add_u32_e32 v0, s1, v58
	ds_read_b64 v[76:77], v0
	v_add_u32_e32 v0, 0x4000, v61
	v_add_u32_e32 v52, 0x4800, v61
	s_addk_i32 s1, 0x1100
	s_cmpk_eq_i32 s1, 0x4400
	s_waitcnt lgkmcnt(0)
	v_mfma_f32_16x16x16_bf16 v[34:37], v[76:77], v[10:11], 0
	v_mfma_f32_16x16x16_bf16 v[72:75], v[76:77], v[18:19], 0
	s_nop 6
	v_mov_b32_e32 v78, v34
	v_mov_b32_e32 v80, v36
	v_mfma_f32_16x16x16_bf16 v[38:41], v[76:77], v[12:13], 0
	v_mfma_f32_16x16x16_bf16 v[64:67], v[76:77], v[14:15], 0
	v_mov_b32_e32 v79, v72
	v_mov_b32_e32 v72, v35
	v_mov_b32_e32 v81, v74
	v_mov_b32_e32 v74, v37
	v_mfma_f32_16x16x16_bf16 v[34:37], v[76:77], v[20:21], 0
	s_nop 1
	v_mov_b32_e32 v82, v38
	v_mfma_f32_16x16x16_bf16 v[68:71], v[76:77], v[16:17], 0
	s_nop 3
	v_mov_b32_e32 v83, v34
	v_mov_b32_e32 v34, v39
	ds_write2_b64 v0, v[72:73], v[34:35] offset0:194 offset1:210
	v_mov_b32_e32 v34, v40
	v_mov_b32_e32 v35, v36
	v_mov_b32_e32 v36, v41
	ds_write2_b64 v52, v[80:81], v[34:35] offset0:4 offset1:20
	ds_write2_b64 v52, v[74:75], v[36:37] offset0:70 offset1:86
	v_mfma_f32_16x16x16_bf16 v[34:37], v[76:77], v[22:23], 0
	v_mov_b32_e32 v72, v64
	v_mov_b32_e32 v64, v66
	v_mov_b32_e32 v66, v68
	v_mfma_f32_16x16x16_bf16 v[38:41], v[76:77], v[24:25], 0
	ds_write2_b64 v0, v[78:79], v[82:83] offset0:128 offset1:144
	s_nop 2
	v_mov_b32_e32 v73, v34
	v_mov_b32_e32 v34, v65
	v_mov_b32_e32 v65, v36
	v_mov_b32_e32 v36, v67
	v_mov_b32_e32 v67, v38
	v_mov_b32_e32 v38, v69
	ds_write2_b64 v0, v[34:35], v[38:39] offset0:226 offset1:242
	v_mov_b32_e32 v34, v70
	v_mov_b32_e32 v35, v40
	v_mov_b32_e32 v40, v71
	ds_write2_b64 v0, v[72:73], v[66:67] offset0:160 offset1:176
	ds_write2_b64 v52, v[64:65], v[34:35] offset0:36 offset1:52
	ds_write2_b64 v52, v[36:37], v[40:41] offset0:102 offset1:118
	s_waitcnt lgkmcnt(0)
	ds_read_b64 v[84:85], v62 offset:17408
	ds_read_b64 v[86:87], v62 offset:17936
	ds_read_b64 v[88:89], v62 offset:18464
	ds_read_b64 v[90:91], v62 offset:18992
	ds_read_b64 v[92:93], v62 offset:19520
	ds_read_b64 v[94:95], v62 offset:20048
	ds_read_b64 v[96:97], v62 offset:20576
	ds_read_b64 v[98:99], v62 offset:21104
	ds_read_b64 v[100:101], v62 offset:21632
	ds_read_b64 v[102:103], v62 offset:22160
	ds_read_b64 v[104:105], v62 offset:22688
	ds_read_b64 v[106:107], v62 offset:23216
	ds_read_b64 v[108:109], v62 offset:23744
	ds_read_b64 v[110:111], v62 offset:24272
	ds_read_b64 v[112:113], v62 offset:24800
	s_waitcnt lgkmcnt(7)
	ds_read_b64 v[114:115], v62 offset:25328
	v_fma_f32 v124, v49, v32, v84
	v_fma_f32 v125, v49, v33, v85
	v_fma_f32 v126, -v48, v33, v124
	v_fma_f32 v127, v48, v32, v125
	v_fma_f32 v124, v49, v126, v86
	v_fma_f32 v125, v49, v127, v87
	v_fma_f32 v32, -v48, v127, v124
	v_fma_f32 v33, v48, v126, v125
	v_fma_f32 v124, v49, v32, v88
	v_fma_f32 v125, v49, v33, v89
	v_fma_f32 v126, -v48, v33, v124
	v_fma_f32 v127, v48, v32, v125
	v_fma_f32 v124, v49, v126, v90
	v_fma_f32 v125, v49, v127, v91
	v_fma_f32 v32, -v48, v127, v124
	v_fma_f32 v33, v48, v126, v125
	v_fma_f32 v124, v49, v32, v92
	v_fma_f32 v125, v49, v33, v93
	v_fma_f32 v126, -v48, v33, v124
	v_fma_f32 v127, v48, v32, v125
	v_fma_f32 v124, v49, v126, v94
	v_fma_f32 v125, v49, v127, v95
	v_fma_f32 v32, -v48, v127, v124
	v_fma_f32 v33, v48, v126, v125
	v_fma_f32 v124, v49, v32, v96
	v_fma_f32 v125, v49, v33, v97
	v_fma_f32 v126, -v48, v33, v124
	v_fma_f32 v127, v48, v32, v125
	v_fma_f32 v124, v49, v126, v98
	v_fma_f32 v125, v49, v127, v99
	v_fma_f32 v32, -v48, v127, v124
	v_fma_f32 v33, v48, v126, v125
	s_waitcnt lgkmcnt(0)
	v_fma_f32 v124, v49, v32, v100
	v_fma_f32 v125, v49, v33, v101
	v_fma_f32 v126, -v48, v33, v124
	v_fma_f32 v127, v48, v32, v125
	v_fma_f32 v124, v49, v126, v102
	v_fma_f32 v125, v49, v127, v103
	v_fma_f32 v32, -v48, v127, v124
	v_fma_f32 v33, v48, v126, v125
	v_fma_f32 v124, v49, v32, v104
	v_fma_f32 v125, v49, v33, v105
	v_fma_f32 v126, -v48, v33, v124
	v_fma_f32 v127, v48, v32, v125
	v_fma_f32 v124, v49, v126, v106
	v_fma_f32 v125, v49, v127, v107
	v_fma_f32 v32, -v48, v127, v124
	v_fma_f32 v33, v48, v126, v125
	v_fma_f32 v124, v49, v32, v108
	v_fma_f32 v125, v49, v33, v109
	v_fma_f32 v126, -v48, v33, v124
	v_fma_f32 v127, v48, v32, v125
	v_fma_f32 v124, v49, v126, v110
	v_fma_f32 v125, v49, v127, v111
	v_fma_f32 v32, -v48, v127, v124
	v_fma_f32 v33, v48, v126, v125
	v_fma_f32 v124, v49, v32, v112
	v_fma_f32 v125, v49, v33, v113
	v_fma_f32 v126, -v48, v33, v124
	v_fma_f32 v127, v48, v32, v125
	v_fma_f32 v124, v49, v126, v114
	v_fma_f32 v125, v49, v127, v115
	v_fma_f32 v32, -v48, v127, v124
	v_fma_f32 v33, v48, v126, v125
	s_cbranch_scc0 .LBB0_296
	s_add_i32 s2, s2, 1
	s_cmp_lg_u32 s2, 8
	s_cbranch_scc1 .LBB0_293
	s_lshl_b32 s0, s25, 4
	s_or_b32 s0, s0, s9
	s_ashr_i32 s1, s0, 31
	s_ashr_i32 s9, s8, 31
	s_lshl_b64 s[0:1], s[0:1], 15
	s_add_u32 s2, s19, s0
	s_addc_u32 s3, s22, s1
	s_lshl_b64 s[0:1], s[8:9], 9
	s_add_u32 s0, s2, s0
	s_addc_u32 s1, s3, s1
	global_store_dwordx2 v63, v[32:33], s[0:1]
	s_branch .LBB0_282
